# GLA output pass: state-fragment loads of k-steps 0..6 issued behind the stage-1 loads (28 in flight), step 7 as soon as step 0 registers free, vmcnt waits regenerated from dependencies; on top of stat
# baseline (speedup 1.0000x reference)
; #define LAS __attribute__((address_space(3)))
; __device__ __forceinline__ bf16* st_ptr(unsigned char* ws, int pu) { return (bf16*)(ws + (pu < 392 ? WS_ST0 + (size_t)pu * 262144 : WS_ST1 + (size_t)(pu - 392) * 262144)); }
; __device__ __forceinline__ void gla_out_unit(const Params& P, LAS unsigned char* lds, int u) {
;     ...
;     const bf16* PROJ = (const bf16*)(ws + WS_PROJ); const bf16* QT = (const bf16*)(ws + WS_QT); const bf16* AM = (const bf16*)(ws + WS_AM); const bf16* VT = (const bf16*)(ws + WS_VT);
;     bf16* OB = (bf16*)(ws + WS_OB); const bf16* ST = st_ptr(ws, u);
;     LAS bf16* QS = (LAS bf16*)lds;
;     LAS bf16* AS = (LAS bf16*)(lds + 33792);
;     LAS float* SS = (LAS float*)(lds + 33792 + 9216);
;     LAS float* RS = (LAS float*)(lds + 33792 + 9216 + 2048);
; #pragma unroll
;     for (int it = 0; it < 4; ++it) { const int idx = it * NTHREADS + tid, t = idx >> 5, cc = idx & 31; *(LAS v4u*)(QS + t * 264 + 8 * cc) = *(const v4u*)(QT + ((size_t)u * 64 + t) * 256 + 8 * cc); }
;     { const int t = tid >> 3, cc = tid & 7; *(LAS v4u*)(AS + t * 72 + 8 * cc) = *(const v4u*)(AM + ((size_t)u * 64 + t) * 64 + 8 * cc); }
;     LAS bf16* RT = (LAS bf16*)(lds + 49152);
; #pragma unroll
;     for (int it = 0; it < 8; ++it) { const int idx = it * NTHREADS + tid, t = idx >> 6, cc = idx & 63; const v4u rv = *(const v4u*)(PROJ + (size_t)(tok0 + t) * LD0 + 4096 + 512 * h + 8 * cc);
;         LAS v2u* d = (LAS v2u*)(RT + t * 516 + 8 * cc); d[0] = (v2u){rv.x, rv.y}; d[1] = (v2u){rv.z, rv.w}; }
;     ...
;     const bf16* stp = ST + ((size_t)(q4 >> 1) * 512 + 64 * wave + fr) * 16 + 8 * (q4 & 1); const bf16* vtp = VT + ((size_t)u * 512 + 64 * wave + fr) * 64 + 8 * q4;
; #pragma unroll
;     for (int kb = 0; kb < 10; ++kb) { bf16x8 bfr[4], afr[4];
; #pragma unroll
;         for (int j = 0; j < 4; ++j) bfr[j] = kb < 8 ? __builtin_nontemporal_load((const bf16x8*)(stp + (size_t)(2 * kb) * 8192 + 16 * j * 16)) : *(const bf16x8*)(vtp + (size_t)(16 * j) * 64 + 32 * (kb - 8));
.LBB0_485:
	s_and_b32 s4, s13, 0xfc0
	s_add_i32 s0, s6, 0xfffffe78
	s_ashr_i32 s7, s6, 31
	s_cmpk_lt_i32 s6, 0x188
	s_cselect_b32 s3, s7, 0
	s_cselect_b32 s2, s6, s0
	s_mov_b32 s0, 0x9200000
	s_cselect_b32 s0, s0, 0x1b800000
	s_lshl_b64 s[2:3], s[2:3], 18
	s_add_u32 s1, s90, s2
	v_mov_b32_e32 v79, v172
	s_addc_u32 s2, s91, s3
	s_lshl_b64 s[26:27], s[6:7], 15
	s_add_u32 s26, s59, s26
	v_lshlrev_b32_e32 v53, 4, v79
	v_add_u32_e32 v81, 0x400, v79
	s_addc_u32 s27, s60, s27
	v_and_b32_e32 v68, 0x1f0, v53
	v_ashrrev_i32_e32 v54, 5, v79
	v_add_u32_e32 v82, 0x200, v79
	v_ashrrev_i32_e32 v58, 5, v81
	s_and_b32 s3, s12, 0xfffff000
	v_ashrrev_i32_e32 v20, 3, v79
	v_lshl_add_u64 v[12:13], s[26:27], 0, v[68:69]
	v_ashrrev_i32_e32 v55, 31, v54
	v_ashrrev_i32_e32 v56, 5, v82
	v_ashrrev_i32_e32 v59, 31, v58
	v_add_u32_e32 v80, 0x600, v79
	s_or_b32 s25, s3, s4
	v_ashrrev_i32_e32 v21, 31, v20
	s_lshl_b64 s[26:27], s[6:7], 13
	s_movk_i32 s3, 0x90
	v_add_u32_e32 v52, 0, v68
	v_lshlrev_b64 v[0:1], 9, v[54:55]
	v_ashrrev_i32_e32 v57, 31, v56
	v_lshlrev_b64 v[8:9], 9, v[58:59]
	v_ashrrev_i32_e32 v60, 5, v80
	s_add_u32 s26, s61, s26
	v_lshlrev_b64 v[16:17], 7, v[20:21]
	v_and_b32_e32 v68, 0x70, v53
	v_mul_lo_u32 v20, v20, s3
	v_ashrrev_i32_e32 v59, 6, v79
	v_lshl_add_u64 v[0:1], v[12:13], 0, v[0:1]
	v_lshlrev_b64 v[4:5], 9, v[56:57]
	v_ashrrev_i32_e32 v61, 31, v60
	s_addc_u32 s27, s62, s27
	v_add3_u32 v57, 0, v20, v68
	s_and_b32 s3, s24, 0x600
	v_add_u32_e32 v20, s25, v59
	global_load_dwordx4 v[0:3], v[0:1], off
	v_lshl_add_u64 v[4:5], v[12:13], 0, v[4:5]
	v_lshlrev_b64 v[14:15], 9, v[60:61]
	v_lshl_add_u64 v[16:17], s[26:27], 0, v[16:17]
	v_mad_i64_i32 v[20:21], s[26:27], v20, s18, v[70:71]
	s_lshl_b32 s4, s3, 1
	v_ashrrev_i32_e32 v61, 6, v82
	global_load_dwordx4 v[4:7], v[4:5], off
	v_lshl_add_u64 v[8:9], v[12:13], 0, v[8:9]
	v_lshl_add_u64 v[16:17], v[16:17], 0, v[68:69]
	v_and_b32_e32 v68, 0x3f0, v53
	v_lshl_add_u64 v[20:21], v[20:21], 0, s[4:5]
	v_add_u32_e32 v24, s25, v61
	global_load_dwordx4 v[8:11], v[8:9], off
	v_lshl_add_u64 v[12:13], v[12:13], 0, v[14:15]
	v_lshl_add_u64 v[20:21], v[20:21], 0, v[68:69]
	v_mad_i64_i32 v[24:25], s[26:27], v24, s18, v[70:71]
	v_ashrrev_i32_e32 v62, 6, v81
	global_load_dwordx4 v[12:15], v[12:13], off
	v_add_co_u32_e32 v20, vcc, s19, v20
	v_lshl_add_u64 v[24:25], v[24:25], 0, s[4:5]
	v_add_u32_e32 v28, s25, v62
	v_addc_co_u32_e32 v21, vcc, 0, v21, vcc
	v_lshl_add_u64 v[24:25], v[24:25], 0, v[68:69]
	v_mad_i64_i32 v[28:29], s[26:27], v28, s18, v[70:71]
	v_ashrrev_i32_e32 v63, 6, v80
	global_load_dwordx4 v[16:19], v[16:17], off
	v_add_co_u32_e32 v24, vcc, s19, v24
	global_load_dwordx4 v[20:23], v[20:21], off
	v_lshl_add_u64 v[28:29], v[28:29], 0, s[4:5]
	v_add_u32_e32 v32, s25, v63
	v_add_u32_e32 v83, 0x800, v79
	v_addc_co_u32_e32 v25, vcc, 0, v25, vcc
	v_lshl_add_u64 v[28:29], v[28:29], 0, v[68:69]
	v_mad_i64_i32 v[32:33], s[26:27], v32, s18, v[70:71]
	v_ashrrev_i32_e32 v64, 6, v83
	global_load_dwordx4 v[24:27], v[24:25], off
	v_add_co_u32_e32 v28, vcc, s19, v28
	v_lshl_add_u64 v[32:33], v[32:33], 0, s[4:5]
	v_add_u32_e32 v36, s25, v64
	v_add_u32_e32 v86, 0xa00, v79
	v_addc_co_u32_e32 v29, vcc, 0, v29, vcc
	v_lshl_add_u64 v[32:33], v[32:33], 0, v[68:69]
	v_mad_i64_i32 v[36:37], s[26:27], v36, s18, v[70:71]
	v_ashrrev_i32_e32 v65, 6, v86
	global_load_dwordx4 v[28:31], v[28:29], off
	v_add_co_u32_e32 v32, vcc, s19, v32
	v_lshl_add_u64 v[36:37], v[36:37], 0, s[4:5]
	v_add_u32_e32 v40, s25, v65
	v_add_u32_e32 v85, 0xc00, v79
	v_addc_co_u32_e32 v33, vcc, 0, v33, vcc
	v_lshl_add_u64 v[36:37], v[36:37], 0, v[68:69]
	v_mad_i64_i32 v[40:41], s[26:27], v40, s18, v[70:71]
	v_ashrrev_i32_e32 v66, 6, v85
	global_load_dwordx4 v[32:35], v[32:33], off
	v_add_co_u32_e32 v36, vcc, s19, v36
	v_lshl_add_u64 v[40:41], v[40:41], 0, s[4:5]
	v_add_u32_e32 v44, s25, v66
	v_add_u32_e32 v84, 0xe00, v79
	v_addc_co_u32_e32 v37, vcc, 0, v37, vcc
	v_lshl_add_u64 v[40:41], v[40:41], 0, v[68:69]
	v_mad_i64_i32 v[44:45], s[26:27], v44, s18, v[70:71]
	v_ashrrev_i32_e32 v67, 6, v84
	global_load_dwordx4 v[36:39], v[36:37], off
	v_add_co_u32_e32 v40, vcc, s19, v40
	v_lshl_add_u64 v[44:45], v[44:45], 0, s[4:5]
	v_add_u32_e32 v48, s25, v67
	v_addc_co_u32_e32 v41, vcc, 0, v41, vcc
	v_lshl_add_u64 v[44:45], v[44:45], 0, v[68:69]
	v_mad_i64_i32 v[48:49], s[26:27], v48, s18, v[70:71]
	global_load_dwordx4 v[40:43], v[40:41], off
	v_add_co_u32_e32 v44, vcc, s19, v44
	v_lshl_add_u64 v[48:49], v[48:49], 0, s[4:5]
	s_nop 0
	v_addc_co_u32_e32 v45, vcc, 0, v45, vcc
	v_lshl_add_u64 v[48:49], v[48:49], 0, v[68:69]
	global_load_dwordx4 v[44:47], v[44:45], off
	v_add_co_u32_e32 v48, vcc, s19, v48
	v_mad_u64_u32 v[54:55], s[26:27], v54, s17, v[52:53]
	s_nop 0
	v_addc_co_u32_e32 v49, vcc, 0, v49, vcc
	global_load_dwordx4 v[48:51], v[48:49], off
	s_add_u32 s28, s1, s0
	s_addc_u32 s29, s2, 0
	v_and_b32_e32 v255, 0xffffffc0, v172
	v_lshlrev_b32_e32 v254, 4, v172
	v_and_b32_e32 v254, 0x200, v254
	v_add_u32_e32 v255, v255, v254
	v_and_b32_e32 v254, 15, v172
	v_or_b32_e32 v255, v255, v254
	v_lshlrev_b32_e32 v255, 5, v255
	v_and_b32_e32 v254, 16, v172
	v_add_u32_e32 v255, v255, v254
	global_load_dwordx4 v[142:145], v255, s[28:29]
	global_load_dwordx4 v[146:149], v255, s[28:29] offset:512
	global_load_dwordx4 v[150:153], v255, s[28:29] offset:1024
	global_load_dwordx4 v[154:157], v255, s[28:29] offset:1536
	v_add_u32_e32 v255, 0x8000, v255
	global_load_dwordx4 v[118:121], v255, s[28:29]
	global_load_dwordx4 v[122:125], v255, s[28:29] offset:512
	global_load_dwordx4 v[130:133], v255, s[28:29] offset:1024
	global_load_dwordx4 v[134:137], v255, s[28:29] offset:1536
	v_add_u32_e32 v255, 0x8000, v255
	global_load_dwordx4 v[138:141], v255, s[28:29]
	global_load_dwordx4 v[158:161], v255, s[28:29] offset:512
	global_load_dwordx4 v[162:165], v255, s[28:29] offset:1024
	global_load_dwordx4 v[166:169], v255, s[28:29] offset:1536
	v_add_u32_e32 v255, 0x8000, v255
	global_load_dwordx4 v[180:183], v255, s[28:29]
	global_load_dwordx4 v[184:187], v255, s[28:29] offset:512
	global_load_dwordx4 v[188:191], v255, s[28:29] offset:1024
	global_load_dwordx4 v[192:195], v255, s[28:29] offset:1536
	v_add_u32_e32 v255, 0x8000, v255
	global_load_dwordx4 v[196:199], v255, s[28:29]
	global_load_dwordx4 v[200:203], v255, s[28:29] offset:512
	global_load_dwordx4 v[204:207], v255, s[28:29] offset:1024
	global_load_dwordx4 v[208:211], v255, s[28:29] offset:1536
	v_add_u32_e32 v255, 0x8000, v255
	global_load_dwordx4 v[212:215], v255, s[28:29]
	global_load_dwordx4 v[216:219], v255, s[28:29] offset:512
	global_load_dwordx4 v[220:223], v255, s[28:29] offset:1024
	global_load_dwordx4 v[224:227], v255, s[28:29] offset:1536
	v_add_u32_e32 v255, 0x8000, v255
	global_load_dwordx4 v[228:231], v255, s[28:29]
	global_load_dwordx4 v[232:235], v255, s[28:29] offset:512
	global_load_dwordx4 v[238:241], v255, s[28:29] offset:1024
	global_load_dwordx4 v[242:245], v255, s[28:29] offset:1536
	v_add_u32_e32 v255, 0x8000, v255
	s_waitcnt vmcnt(40)
; #define LAS __attribute__((address_space(3)))
; __device__ __forceinline__ void gla_out_unit(const Params& P, LAS unsigned char* lds, int u) {
;     ...
;     for (int it = 0; it < 4; ++it) { const int idx = it * NTHREADS + tid, t = idx >> 5, cc = idx & 31; *(LAS v4u*)(QS + t * 264 + 8 * cc) = *(const v4u*)(QT + ((size_t)u * 64 + t) * 256 + 8 * cc); }
;     { const int t = tid >> 3, cc = tid & 7; *(LAS v4u*)(AS + t * 72 + 8 * cc) = *(const v4u*)(AM + ((size_t)u * 64 + t) * 64 + 8 * cc); }
;     LAS bf16* RT = (LAS bf16*)(lds + 49152);
; #pragma unroll
;     for (int it = 0; it < 8; ++it) { const int idx = it * NTHREADS + tid, t = idx >> 6, cc = idx & 63; const v4u rv = *(const v4u*)(PROJ + (size_t)(tok0 + t) * LD0 + 4096 + 512 * h + 8 * cc);
;         LAS v2u* d = (LAS v2u*)(RT + t * 516 + 8 * cc); d[0] = (v2u){rv.x, rv.y}; d[1] = (v2u){rv.z, rv.w}; }
;     __syncthreads();
;     f32x4 acc[4][4];
; #pragma unroll
;     for (int m = 0; m < 4; ++m)
; #pragma unroll
;         for (int j = 0; j < 4; ++j) acc[m][j] = (f32x4){0.f, 0.f, 0.f, 0.f};
;     const bf16* stp = ST + ((size_t)(q4 >> 1) * 512 + 64 * wave + fr) * 16 + 8 * (q4 & 1); const bf16* vtp = VT + ((size_t)u * 512 + 64 * wave + fr) * 64 + 8 * q4;
; #pragma unroll
;     for (int kb = 0; kb < 10; ++kb) { bf16x8 bfr[4], afr[4];
; #pragma unroll
;         for (int j = 0; j < 4; ++j) bfr[j] = kb < 8 ? __builtin_nontemporal_load((const bf16x8*)(stp + (size_t)(2 * kb) * 8192 + 16 * j * 16)) : *(const bf16x8*)(vtp + (size_t)(16 * j) * 64 + 32 * (kb - 8));
; #pragma unroll
;         for (int m = 0; m < 4; ++m) afr[m] = kb < 8 ? *(const LAS bf16x8*)(QS + (16 * m + fr) * 264 + 32 * kb + 8 * q4) : *(const LAS bf16x8*)(AS + (16 * m + fr) * 72 + 32 * (kb - 8) + 8 * q4);
; #pragma unroll
;         for (int m = 0; m < 4; ++m)
; #pragma unroll
;             for (int j = 0; j < 4; ++j) acc[m][j] = __builtin_amdgcn_mfma_f32_16x16x32_bf16(afr[m], bfr[j], acc[m][j], 0, 0, 0); }
	ds_write_b128 v54, v[0:3]
	v_mad_u64_u32 v[0:1], s[26:27], v56, s17, v[52:53]
	s_waitcnt vmcnt(39)
	ds_write_b128 v0, v[4:7]
	v_mad_u64_u32 v[0:1], s[26:27], v58, s17, v[52:53]
	s_waitcnt vmcnt(38)
	ds_write_b128 v0, v[8:11]
	v_mad_u64_u32 v[0:1], s[26:27], v60, s17, v[52:53]
	s_waitcnt vmcnt(37)
	ds_write_b128 v0, v[12:15]
	v_add_u32_e32 v0, 0, v68
	v_mul_lo_u32 v1, v59, s20
	v_add3_u32 v1, v0, v1, s21
	s_waitcnt vmcnt(36)
	ds_write_b128 v57, v[16:19] offset:33792
	s_waitcnt vmcnt(35)
	ds_write2_b64 v1, v[20:21], v[22:23] offset1:1
	v_mul_lo_u32 v1, v61, s20
	v_add3_u32 v1, v0, v1, s21
	v_and_b32_e32 v72, 0xffffffc0, v79
	v_and_b32_e32 v68, 0x200, v53
	s_waitcnt vmcnt(34)
	ds_write2_b64 v1, v[24:25], v[26:27] offset1:1
	v_mul_lo_u32 v1, v62, s20
	v_add3_u32 v1, v0, v1, s21
	v_ashrrev_i32_e32 v73, 31, v72
	v_and_b32_e32 v91, 15, v79
	s_add_u32 s0, s1, s0
	s_addc_u32 s1, s2, 0
	v_bfe_u32 v92, v79, 4, 2
	s_waitcnt vmcnt(33)
	ds_write2_b64 v1, v[28:29], v[30:31] offset1:1
	v_mul_lo_u32 v1, v63, s20
	v_add3_u32 v1, v0, v1, s21
	s_waitcnt vmcnt(32)
	ds_write2_b64 v1, v[32:33], v[34:35] offset1:1
	v_mul_lo_u32 v1, v64, s20
	v_add3_u32 v1, v0, v1, s21
	s_waitcnt vmcnt(31)
	ds_write2_b64 v1, v[36:37], v[38:39] offset1:1
	v_mul_lo_u32 v1, v65, s20
	v_add3_u32 v1, v0, v1, s21
	s_waitcnt vmcnt(30)
	ds_write2_b64 v1, v[40:41], v[42:43] offset1:1
	v_mul_lo_u32 v1, v66, s20
	v_add3_u32 v1, v0, v1, s21
	s_waitcnt vmcnt(29)
	ds_write2_b64 v1, v[44:45], v[46:47] offset1:1
	v_mul_lo_u32 v1, v67, s20
	v_add3_u32 v0, v0, v1, s21
	s_waitcnt vmcnt(28)
	ds_write2_b64 v0, v[48:49], v[50:51] offset1:1
	v_lshl_add_u64 v[0:1], v[68:69], 0, v[72:73]
	v_or_b32_e32 v0, v0, v91
	v_lshlrev_b64 v[0:1], 5, v[0:1]
	v_lshl_add_u64 v[0:1], s[0:1], 0, v[0:1]
	v_and_b32_e32 v68, 16, v79
	v_lshl_add_u64 v[16:17], v[0:1], 0, v[68:69]
	s_waitcnt lgkmcnt(0)
	s_barrier
	v_lshlrev_b32_e32 v68, 4, v92
	v_add_u32_e32 v87, 0, v68
	v_mad_u32_u24 v18, v91, s17, v87
	ds_read_b128 v[4:7], v18
	ds_read_b128 v[98:101], v18 offset:25344
	s_waitcnt lgkmcnt(1)
	s_waitcnt vmcnt(27)
	v_mfma_f32_16x16x32_bf16 v[20:23], v[4:7], v[142:145], 0
	s_mov_b32 s0, 0x8000
	v_add_co_u32_e32 v88, vcc, s0, v16
	s_waitcnt vmcnt(26)
	v_mfma_f32_16x16x32_bf16 v[24:27], v[4:7], v[146:149], 0
	v_addc_co_u32_e32 v89, vcc, 0, v17, vcc
	s_waitcnt vmcnt(25)
	v_mfma_f32_16x16x32_bf16 v[28:31], v[4:7], v[150:153], 0
	ds_read_b128 v[114:117], v18 offset:25792
	s_waitcnt vmcnt(24)
	v_mfma_f32_16x16x32_bf16 v[36:39], v[4:7], v[154:157], 0
	ds_read_b128 v[4:7], v18 offset:8448
	s_mov_b32 s0, 0x10000
	s_waitcnt lgkmcnt(0)
	v_mfma_f32_16x16x32_bf16 v[40:43], v[4:7], v[142:145], 0
	v_mfma_f32_16x16x32_bf16 v[44:47], v[4:7], v[146:149], 0
	v_mfma_f32_16x16x32_bf16 v[48:51], v[4:7], v[150:153], 0
	v_mfma_f32_16x16x32_bf16 v[52:55], v[4:7], v[154:157], 0
	ds_read_b128 v[4:7], v18 offset:16896
	s_waitcnt lgkmcnt(0)
	v_mfma_f32_16x16x32_bf16 v[56:59], v[4:7], v[142:145], 0
	v_mfma_f32_16x16x32_bf16 v[60:63], v[4:7], v[146:149], 0
	v_mfma_f32_16x16x32_bf16 v[64:67], v[4:7], v[150:153], 0
	v_mfma_f32_16x16x32_bf16 v[94:97], v[4:7], v[154:157], 0
	v_mfma_f32_16x16x32_bf16 v[4:7], v[98:101], v[142:145], 0
	v_mfma_f32_16x16x32_bf16 v[8:11], v[98:101], v[146:149], 0
	v_mfma_f32_16x16x32_bf16 v[12:15], v[98:101], v[150:153], 0
	v_mfma_f32_16x16x32_bf16 v[0:3], v[98:101], v[154:157], 0
	global_load_dwordx4 v[142:145], v255, s[28:29]
	global_load_dwordx4 v[146:149], v255, s[28:29] offset:512
	global_load_dwordx4 v[150:153], v255, s[28:29] offset:1024
	global_load_dwordx4 v[154:157], v255, s[28:29] offset:1536
	ds_read_b128 v[32:35], v18 offset:64
	v_add_co_u32_e32 v88, vcc, s0, v16
	s_waitcnt lgkmcnt(0)
	s_waitcnt vmcnt(27)
	v_mfma_f32_16x16x32_bf16 v[20:23], v[32:35], v[118:121], v[20:23]
	v_addc_co_u32_e32 v89, vcc, 0, v17, vcc
	s_mov_b32 s0, 0x18000
	s_waitcnt vmcnt(26)
	v_mfma_f32_16x16x32_bf16 v[24:27], v[32:35], v[122:125], v[24:27]
	s_waitcnt vmcnt(25)
	v_mfma_f32_16x16x32_bf16 v[28:31], v[32:35], v[130:133], v[28:31]
	s_waitcnt vmcnt(24)
	v_mfma_f32_16x16x32_bf16 v[32:35], v[32:35], v[134:137], v[36:39]
	s_nop 2
	ds_read_b128 v[36:39], v18 offset:8512
	s_waitcnt lgkmcnt(0)
	v_mfma_f32_16x16x32_bf16 v[40:43], v[36:39], v[118:121], v[40:43]
	v_mfma_f32_16x16x32_bf16 v[44:47], v[36:39], v[122:125], v[44:47]
	v_mfma_f32_16x16x32_bf16 v[48:51], v[36:39], v[130:133], v[48:51]
	v_mfma_f32_16x16x32_bf16 v[36:39], v[36:39], v[134:137], v[52:55]
	s_nop 2
	ds_read_b128 v[52:55], v18 offset:16960
	s_waitcnt lgkmcnt(0)
	v_mfma_f32_16x16x32_bf16 v[56:59], v[52:55], v[118:121], v[56:59]
	v_mfma_f32_16x16x32_bf16 v[60:63], v[52:55], v[122:125], v[60:63]
	v_mfma_f32_16x16x32_bf16 v[64:67], v[52:55], v[130:133], v[64:67]
	v_mfma_f32_16x16x32_bf16 v[52:55], v[52:55], v[134:137], v[94:97]
	s_nop 2
	ds_read_b128 v[94:97], v18 offset:25408
	s_waitcnt lgkmcnt(0)
	v_mfma_f32_16x16x32_bf16 v[4:7], v[94:97], v[118:121], v[4:7]
	v_mfma_f32_16x16x32_bf16 v[8:11], v[94:97], v[122:125], v[8:11]
	v_mfma_f32_16x16x32_bf16 v[12:15], v[94:97], v[130:133], v[12:15]
	v_mfma_f32_16x16x32_bf16 v[0:3], v[94:97], v[134:137], v[0:3]
	ds_read_b128 v[94:97], v18 offset:128
	v_add_co_u32_e32 v88, vcc, s0, v16
	s_waitcnt lgkmcnt(0)
	s_waitcnt vmcnt(23)
	v_mfma_f32_16x16x32_bf16 v[20:23], v[94:97], v[138:141], v[20:23]
	v_addc_co_u32_e32 v89, vcc, 0, v17, vcc
	s_mov_b32 s0, 0x20000
	s_waitcnt vmcnt(22)
	v_mfma_f32_16x16x32_bf16 v[24:27], v[94:97], v[158:161], v[24:27]
	s_waitcnt vmcnt(21)
	v_mfma_f32_16x16x32_bf16 v[28:31], v[94:97], v[162:165], v[28:31]
	s_waitcnt vmcnt(20)
	v_mfma_f32_16x16x32_bf16 v[32:35], v[94:97], v[166:169], v[32:35]
	ds_read_b128 v[94:97], v18 offset:8576
	s_waitcnt lgkmcnt(0)
; #define LAS __attribute__((address_space(3)))
; __device__ __forceinline__ void gla_out_unit(const Params& P, LAS unsigned char* lds, int u) {
;     ...
;     for (int kb = 0; kb < 10; ++kb) { bf16x8 bfr[4], afr[4];
; #pragma unroll
;         for (int j = 0; j < 4; ++j) bfr[j] = kb < 8 ? __builtin_nontemporal_load((const bf16x8*)(stp + (size_t)(2 * kb) * 8192 + 16 * j * 16)) : *(const bf16x8*)(vtp + (size_t)(16 * j) * 64 + 32 * (kb - 8));
; #pragma unroll
;         for (int m = 0; m < 4; ++m) afr[m] = kb < 8 ? *(const LAS bf16x8*)(QS + (16 * m + fr) * 264 + 32 * kb + 8 * q4) : *(const LAS bf16x8*)(AS + (16 * m + fr) * 72 + 32 * (kb - 8) + 8 * q4);
; #pragma unroll
;         for (int m = 0; m < 4; ++m)
; #pragma unroll
;             for (int j = 0; j < 4; ++j) acc[m][j] = __builtin_amdgcn_mfma_f32_16x16x32_bf16(afr[m], bfr[j], acc[m][j], 0, 0, 0); }
	v_mfma_f32_16x16x32_bf16 v[40:43], v[94:97], v[138:141], v[40:43]
	v_mfma_f32_16x16x32_bf16 v[44:47], v[94:97], v[158:161], v[44:47]
	v_mfma_f32_16x16x32_bf16 v[48:51], v[94:97], v[162:165], v[48:51]
	v_mfma_f32_16x16x32_bf16 v[36:39], v[94:97], v[166:169], v[36:39]
	ds_read_b128 v[94:97], v18 offset:17024
	s_waitcnt lgkmcnt(0)
	v_mfma_f32_16x16x32_bf16 v[56:59], v[94:97], v[138:141], v[56:59]
	v_mfma_f32_16x16x32_bf16 v[60:63], v[94:97], v[158:161], v[60:63]
	v_mfma_f32_16x16x32_bf16 v[64:67], v[94:97], v[162:165], v[64:67]
	v_mfma_f32_16x16x32_bf16 v[52:55], v[94:97], v[166:169], v[52:55]
	ds_read_b128 v[94:97], v18 offset:25472
	s_waitcnt lgkmcnt(0)
	v_mfma_f32_16x16x32_bf16 v[4:7], v[94:97], v[138:141], v[4:7]
	v_mfma_f32_16x16x32_bf16 v[8:11], v[94:97], v[158:161], v[8:11]
	v_mfma_f32_16x16x32_bf16 v[12:15], v[94:97], v[162:165], v[12:15]
	v_mfma_f32_16x16x32_bf16 v[0:3], v[94:97], v[166:169], v[0:3]
	ds_read_b128 v[94:97], v18 offset:192
	v_add_co_u32_e32 v88, vcc, s0, v16
	s_waitcnt lgkmcnt(0)
	s_waitcnt vmcnt(19)
	v_mfma_f32_16x16x32_bf16 v[20:23], v[94:97], v[180:183], v[20:23]
	v_addc_co_u32_e32 v89, vcc, 0, v17, vcc
	s_mov_b32 s0, 0x28000
	s_waitcnt vmcnt(18)
	v_mfma_f32_16x16x32_bf16 v[24:27], v[94:97], v[184:187], v[24:27]
	s_waitcnt vmcnt(17)
	v_mfma_f32_16x16x32_bf16 v[28:31], v[94:97], v[188:191], v[28:31]
	s_waitcnt vmcnt(16)
	v_mfma_f32_16x16x32_bf16 v[32:35], v[94:97], v[192:195], v[32:35]
	ds_read_b128 v[94:97], v18 offset:8640
	s_waitcnt lgkmcnt(0)
	v_mfma_f32_16x16x32_bf16 v[40:43], v[94:97], v[180:183], v[40:43]
	v_mfma_f32_16x16x32_bf16 v[44:47], v[94:97], v[184:187], v[44:47]
	v_mfma_f32_16x16x32_bf16 v[48:51], v[94:97], v[188:191], v[48:51]
	v_mfma_f32_16x16x32_bf16 v[36:39], v[94:97], v[192:195], v[36:39]
	ds_read_b128 v[94:97], v18 offset:17088
	s_waitcnt lgkmcnt(0)
	v_mfma_f32_16x16x32_bf16 v[56:59], v[94:97], v[180:183], v[56:59]
	v_mfma_f32_16x16x32_bf16 v[60:63], v[94:97], v[184:187], v[60:63]
	v_mfma_f32_16x16x32_bf16 v[64:67], v[94:97], v[188:191], v[64:67]
	v_mfma_f32_16x16x32_bf16 v[52:55], v[94:97], v[192:195], v[52:55]
	ds_read_b128 v[94:97], v18 offset:25536
	s_waitcnt lgkmcnt(0)
	v_mfma_f32_16x16x32_bf16 v[4:7], v[94:97], v[180:183], v[4:7]
	v_mfma_f32_16x16x32_bf16 v[8:11], v[94:97], v[184:187], v[8:11]
	v_mfma_f32_16x16x32_bf16 v[12:15], v[94:97], v[188:191], v[12:15]
	v_mfma_f32_16x16x32_bf16 v[0:3], v[94:97], v[192:195], v[0:3]
	ds_read_b128 v[94:97], v18 offset:256
	v_add_co_u32_e32 v88, vcc, s0, v16
	s_waitcnt lgkmcnt(0)
	s_waitcnt vmcnt(15)
	v_mfma_f32_16x16x32_bf16 v[20:23], v[94:97], v[196:199], v[20:23]
	v_addc_co_u32_e32 v89, vcc, 0, v17, vcc
	s_mov_b32 s0, 0x30000
	s_waitcnt vmcnt(14)
	v_mfma_f32_16x16x32_bf16 v[24:27], v[94:97], v[200:203], v[24:27]
	s_waitcnt vmcnt(13)
	v_mfma_f32_16x16x32_bf16 v[28:31], v[94:97], v[204:207], v[28:31]
	s_waitcnt vmcnt(12)
	v_mfma_f32_16x16x32_bf16 v[32:35], v[94:97], v[208:211], v[32:35]
	ds_read_b128 v[94:97], v18 offset:8704
	s_waitcnt lgkmcnt(0)
	v_mfma_f32_16x16x32_bf16 v[40:43], v[94:97], v[196:199], v[40:43]
	v_mfma_f32_16x16x32_bf16 v[44:47], v[94:97], v[200:203], v[44:47]
	v_mfma_f32_16x16x32_bf16 v[48:51], v[94:97], v[204:207], v[48:51]
	v_mfma_f32_16x16x32_bf16 v[36:39], v[94:97], v[208:211], v[36:39]
	ds_read_b128 v[94:97], v18 offset:17152
	s_waitcnt lgkmcnt(0)
	v_mfma_f32_16x16x32_bf16 v[56:59], v[94:97], v[196:199], v[56:59]
	v_mfma_f32_16x16x32_bf16 v[60:63], v[94:97], v[200:203], v[60:63]
	v_mfma_f32_16x16x32_bf16 v[64:67], v[94:97], v[204:207], v[64:67]
	v_mfma_f32_16x16x32_bf16 v[52:55], v[94:97], v[208:211], v[52:55]
	ds_read_b128 v[94:97], v18 offset:25600
	s_waitcnt lgkmcnt(0)
	v_mfma_f32_16x16x32_bf16 v[4:7], v[94:97], v[196:199], v[4:7]
	v_mfma_f32_16x16x32_bf16 v[8:11], v[94:97], v[200:203], v[8:11]
	v_mfma_f32_16x16x32_bf16 v[12:15], v[94:97], v[204:207], v[12:15]
	v_mfma_f32_16x16x32_bf16 v[0:3], v[94:97], v[208:211], v[0:3]
	ds_read_b128 v[94:97], v18 offset:320
	v_add_co_u32_e32 v88, vcc, s0, v16
	s_waitcnt lgkmcnt(0)
	s_waitcnt vmcnt(11)
	v_mfma_f32_16x16x32_bf16 v[20:23], v[94:97], v[212:215], v[20:23]
	v_addc_co_u32_e32 v89, vcc, 0, v17, vcc
	s_mov_b32 s0, 0x38000
	s_waitcnt vmcnt(10)
	v_mfma_f32_16x16x32_bf16 v[24:27], v[94:97], v[216:219], v[24:27]
	v_add_co_u32_e32 v16, vcc, s0, v16
	s_lshl_b64 s[0:1], s[6:7], 9
	s_waitcnt vmcnt(9)
	v_mfma_f32_16x16x32_bf16 v[28:31], v[94:97], v[220:223], v[28:31]
	v_addc_co_u32_e32 v17, vcc, 0, v17, vcc
	s_waitcnt vmcnt(8)
	v_mfma_f32_16x16x32_bf16 v[32:35], v[94:97], v[224:227], v[32:35]
	ds_read_b128 v[94:97], v18 offset:8768
	s_waitcnt lgkmcnt(0)
	v_mfma_f32_16x16x32_bf16 v[40:43], v[94:97], v[212:215], v[40:43]
	v_mfma_f32_16x16x32_bf16 v[44:47], v[94:97], v[216:219], v[44:47]
	v_mfma_f32_16x16x32_bf16 v[48:51], v[94:97], v[220:223], v[48:51]
	v_mfma_f32_16x16x32_bf16 v[36:39], v[94:97], v[224:227], v[36:39]
	ds_read_b128 v[94:97], v18 offset:17216
	s_waitcnt lgkmcnt(0)
	v_mfma_f32_16x16x32_bf16 v[56:59], v[94:97], v[212:215], v[56:59]
	v_mfma_f32_16x16x32_bf16 v[60:63], v[94:97], v[216:219], v[60:63]
	v_mfma_f32_16x16x32_bf16 v[64:67], v[94:97], v[220:223], v[64:67]
	v_mfma_f32_16x16x32_bf16 v[52:55], v[94:97], v[224:227], v[52:55]
	ds_read_b128 v[94:97], v18 offset:25664
	s_waitcnt lgkmcnt(0)
	v_mfma_f32_16x16x32_bf16 v[4:7], v[94:97], v[212:215], v[4:7]
	v_mfma_f32_16x16x32_bf16 v[8:11], v[94:97], v[216:219], v[8:11]
	v_mfma_f32_16x16x32_bf16 v[12:15], v[94:97], v[220:223], v[12:15]
	v_mfma_f32_16x16x32_bf16 v[0:3], v[94:97], v[224:227], v[0:3]
	ds_read_b128 v[94:97], v18 offset:384
	s_waitcnt lgkmcnt(0)
	s_waitcnt vmcnt(7)
	v_mfma_f32_16x16x32_bf16 v[20:23], v[94:97], v[228:231], v[20:23]
	s_waitcnt vmcnt(6)
; #define LAS __attribute__((address_space(3)))
; __device__ __forceinline__ void gla_out_unit(const Params& P, LAS unsigned char* lds, int u) {
;     ...
;     for (int kb = 0; kb < 10; ++kb) { bf16x8 bfr[4], afr[4];
; #pragma unroll
;         for (int j = 0; j < 4; ++j) bfr[j] = kb < 8 ? __builtin_nontemporal_load((const bf16x8*)(stp + (size_t)(2 * kb) * 8192 + 16 * j * 16)) : *(const bf16x8*)(vtp + (size_t)(16 * j) * 64 + 32 * (kb - 8));
; #pragma unroll
;         for (int m = 0; m < 4; ++m) afr[m] = kb < 8 ? *(const LAS bf16x8*)(QS + (16 * m + fr) * 264 + 32 * kb + 8 * q4) : *(const LAS bf16x8*)(AS + (16 * m + fr) * 72 + 32 * (kb - 8) + 8 * q4);
; #pragma unroll
;         for (int m = 0; m < 4; ++m)
; #pragma unroll
;             for (int j = 0; j < 4; ++j) acc[m][j] = __builtin_amdgcn_mfma_f32_16x16x32_bf16(afr[m], bfr[j], acc[m][j], 0, 0, 0); }
	v_mfma_f32_16x16x32_bf16 v[24:27], v[94:97], v[232:235], v[24:27]
	s_waitcnt vmcnt(5)
	v_mfma_f32_16x16x32_bf16 v[28:31], v[94:97], v[238:241], v[28:31]
	s_waitcnt vmcnt(4)
	v_mfma_f32_16x16x32_bf16 v[32:35], v[94:97], v[242:245], v[32:35]
	ds_read_b128 v[94:97], v18 offset:8832
	s_waitcnt lgkmcnt(0)
	v_mfma_f32_16x16x32_bf16 v[40:43], v[94:97], v[228:231], v[40:43]
	v_mfma_f32_16x16x32_bf16 v[44:47], v[94:97], v[232:235], v[44:47]
	v_mfma_f32_16x16x32_bf16 v[48:51], v[94:97], v[238:241], v[48:51]
	v_mfma_f32_16x16x32_bf16 v[36:39], v[94:97], v[242:245], v[36:39]
	ds_read_b128 v[94:97], v18 offset:17280
	s_waitcnt lgkmcnt(0)
	v_mfma_f32_16x16x32_bf16 v[56:59], v[94:97], v[228:231], v[56:59]
	v_mfma_f32_16x16x32_bf16 v[60:63], v[94:97], v[232:235], v[60:63]
	v_mfma_f32_16x16x32_bf16 v[64:67], v[94:97], v[238:241], v[64:67]
	v_mfma_f32_16x16x32_bf16 v[52:55], v[94:97], v[242:245], v[52:55]
	ds_read_b128 v[94:97], v18 offset:25728
	s_waitcnt lgkmcnt(0)
	v_mfma_f32_16x16x32_bf16 v[98:101], v[94:97], v[228:231], v[4:7]
	v_mfma_f32_16x16x32_bf16 v[8:11], v[94:97], v[232:235], v[8:11]
	v_mfma_f32_16x16x32_bf16 v[4:7], v[94:97], v[238:241], v[12:15]
	s_nop 1
	v_mfma_f32_16x16x32_bf16 v[0:3], v[94:97], v[242:245], v[0:3]
	ds_read_b128 v[94:97], v18 offset:448
	v_lshl_add_u64 v[16:17], s[0:1], 0, v[72:73]
	s_waitcnt lgkmcnt(0)
	s_waitcnt vmcnt(3)
	v_mfma_f32_16x16x32_bf16 v[20:23], v[94:97], v[142:145], v[20:23]
	v_or_b32_e32 v16, v16, v91
	v_lshlrev_b64 v[16:17], 7, v[16:17]
	v_lshl_add_u64 v[16:17], s[90:91], 0, v[16:17]
	s_waitcnt vmcnt(2)
	v_mfma_f32_16x16x32_bf16 v[24:27], v[94:97], v[146:149], v[24:27]
	v_lshl_add_u64 v[16:17], v[16:17], 0, v[68:69]
	s_mov_b32 s0, 0x17401000
	v_add_co_u32_e32 v88, vcc, s0, v16
	s_waitcnt vmcnt(1)
	v_mfma_f32_16x16x32_bf16 v[28:31], v[94:97], v[150:153], v[28:31]
	s_nop 0
	v_addc_co_u32_e32 v89, vcc, 0, v17, vcc
	s_mov_b32 s0, 0x17400000
	s_waitcnt vmcnt(0)
	v_mfma_f32_16x16x32_bf16 v[32:35], v[94:97], v[154:157], v[32:35]
	ds_read_b128 v[94:97], v18 offset:8896
	v_add_co_u32_e32 v126, vcc, s0, v16
	s_waitcnt lgkmcnt(0)
	v_mfma_f32_16x16x32_bf16 v[40:43], v[94:97], v[142:145], v[40:43]
	v_addc_co_u32_e32 v127, vcc, 0, v17, vcc
	v_mad_i32_i24 v68, v91, s22, v18
	v_mfma_f32_16x16x32_bf16 v[44:47], v[94:97], v[146:149], v[44:47]
	v_cmp_lt_i32_e32 vcc, v176, v177
	v_mfma_f32_16x16x32_bf16 v[48:51], v[94:97], v[150:153], v[48:51]
	v_mfma_f32_16x16x32_bf16 v[36:39], v[94:97], v[154:157], v[36:39]
	ds_read_b128 v[94:97], v18 offset:17344
	s_waitcnt lgkmcnt(0)
	v_mfma_f32_16x16x32_bf16 v[56:59], v[94:97], v[142:145], v[56:59]
	v_mfma_f32_16x16x32_bf16 v[60:63], v[94:97], v[146:149], v[60:63]
	v_mfma_f32_16x16x32_bf16 v[64:67], v[94:97], v[150:153], v[64:67]
	v_mfma_f32_16x16x32_bf16 v[52:55], v[94:97], v[154:157], v[52:55]
	global_load_dwordx4 v[94:97], v[88:89], off offset:-4096
	v_mfma_f32_16x16x32_bf16 v[12:15], v[114:117], v[142:145], v[98:101]
	v_mfma_f32_16x16x32_bf16 v[8:11], v[114:117], v[146:149], v[8:11]
	global_load_dwordx4 v[102:105], v[126:127], off offset:2048
	v_mfma_f32_16x16x32_bf16 v[98:101], v[114:117], v[150:153], v[4:7]
	global_load_dwordx4 v[106:109], v[88:89], off
	v_mfma_f32_16x16x32_bf16 v[0:3], v[114:117], v[154:157], v[0:3]
	global_load_dwordx4 v[114:117], v[88:89], off offset:2048
	ds_read_b128 v[4:7], v68 offset:33792
	s_waitcnt lgkmcnt(0)
	s_waitcnt vmcnt(3)
	v_mfma_f32_16x16x32_bf16 v[20:23], v[4:7], v[94:97], v[20:23]
	s_waitcnt vmcnt(2)
	v_mfma_f32_16x16x32_bf16 v[24:27], v[4:7], v[102:105], v[24:27]
	s_waitcnt vmcnt(1)
	v_mfma_f32_16x16x32_bf16 v[110:113], v[4:7], v[106:109], v[28:31]
	s_waitcnt vmcnt(0)
; #define LAS __attribute__((address_space(3)))
; __device__ __forceinline__ void gla_out_unit(const Params& P, LAS unsigned char* lds, int u) {
;     ...
;     for (int kb = 0; kb < 10; ++kb) { bf16x8 bfr[4], afr[4];
; #pragma unroll
;         for (int j = 0; j < 4; ++j) bfr[j] = kb < 8 ? __builtin_nontemporal_load((const bf16x8*)(stp + (size_t)(2 * kb) * 8192 + 16 * j * 16)) : *(const bf16x8*)(vtp + (size_t)(16 * j) * 64 + 32 * (kb - 8));
; #pragma unroll
;         for (int m = 0; m < 4; ++m) afr[m] = kb < 8 ? *(const LAS bf16x8*)(QS + (16 * m + fr) * 264 + 32 * kb + 8 * q4) : *(const LAS bf16x8*)(AS + (16 * m + fr) * 72 + 32 * (kb - 8) + 8 * q4);
; #pragma unroll
;         for (int m = 0; m < 4; ++m)
; #pragma unroll
;             for (int j = 0; j < 4; ++j) acc[m][j] = __builtin_amdgcn_mfma_f32_16x16x32_bf16(afr[m], bfr[j], acc[m][j], 0, 0, 0); }
; #pragma unroll
;     for (int m = 0; m < 4; ++m)
; #pragma unroll
;         for (int i = 0; i < 4; ++i) { float s = 0.f;
; #pragma unroll
;             for (int j = 0; j < 4; ++j) s += acc[m][j][i] * acc[m][j][i];
;             s += __shfl_xor(s, 1); s += __shfl_xor(s, 2); s += __shfl_xor(s, 4); s += __shfl_xor(s, 8);
;             if (fr == 0) SS[wave * 64 + 16 * m + 4 * q4 + i] = s; }
	v_mfma_f32_16x16x32_bf16 v[32:35], v[4:7], v[114:117], v[32:35]
	ds_read_b128 v[4:7], v68 offset:36096
	s_waitcnt lgkmcnt(0)
	v_mfma_f32_16x16x32_bf16 v[40:43], v[4:7], v[94:97], v[40:43]
	v_mfma_f32_16x16x32_bf16 v[118:121], v[4:7], v[102:105], v[44:47]
	v_mfma_f32_16x16x32_bf16 v[122:125], v[4:7], v[106:109], v[48:51]
	v_mfma_f32_16x16x32_bf16 v[130:133], v[4:7], v[114:117], v[36:39]
	ds_read_b128 v[4:7], v68 offset:38400
	s_nop 1
	ds_read_b128 v[36:39], v68 offset:40704
	s_waitcnt lgkmcnt(1)
	v_mfma_f32_16x16x32_bf16 v[28:31], v[4:7], v[106:109], v[64:67]
	s_nop 2
	global_load_dwordx4 v[64:67], v[126:127], off offset:64
	v_mfma_f32_16x16x32_bf16 v[134:137], v[4:7], v[94:97], v[56:59]
	s_waitcnt lgkmcnt(0)
	v_mfma_f32_16x16x32_bf16 v[12:15], v[36:39], v[94:97], v[12:15]
	global_load_dwordx4 v[94:97], v[126:127], off offset:2112
	v_mfma_f32_16x16x32_bf16 v[138:141], v[4:7], v[102:105], v[60:63]
	v_mfma_f32_16x16x32_bf16 v[16:19], v[4:7], v[114:117], v[52:55]
	v_mfma_f32_16x16x32_bf16 v[4:7], v[36:39], v[102:105], v[8:11]
	global_load_dwordx4 v[102:105], v[88:89], off offset:2112
	v_mfma_f32_16x16x32_bf16 v[8:11], v[36:39], v[106:109], v[98:101]
	s_nop 2
	global_load_dwordx4 v[98:101], v[88:89], off offset:64
	v_mfma_f32_16x16x32_bf16 v[0:3], v[36:39], v[114:117], v[0:3]
	ds_read_b128 v[36:39], v68 offset:33856
	s_waitcnt lgkmcnt(0)
	s_waitcnt vmcnt(3)
	v_mfma_f32_16x16x32_bf16 v[56:59], v[36:39], v[64:67], v[20:23]
	s_nop 2
	ds_read_b128 v[20:23], v68 offset:36160
	s_waitcnt vmcnt(2)
	v_mfma_f32_16x16x32_bf16 v[52:55], v[36:39], v[94:97], v[24:27]
	s_waitcnt vmcnt(0)
	v_mfma_f32_16x16x32_bf16 v[60:63], v[36:39], v[98:101], v[110:113]
	s_nop 5
	v_mul_f32_e32 v88, v52, v52
	v_fmac_f32_e32 v88, v56, v56
	ds_read_b128 v[106:109], v68 offset:38464
	ds_read_b128 v[110:113], v68 offset:40768
	v_mfma_f32_16x16x32_bf16 v[48:51], v[36:39], v[102:105], v[32:35]
	v_fmac_f32_e32 v88, v60, v60
	s_waitcnt lgkmcnt(2)
	v_mfma_f32_16x16x32_bf16 v[44:47], v[20:23], v[64:67], v[40:43]
	v_mfma_f32_16x16x32_bf16 v[40:43], v[20:23], v[94:97], v[118:121]
	s_nop 3
	v_fmac_f32_e32 v88, v48, v48
	v_mfma_f32_16x16x32_bf16 v[36:39], v[20:23], v[98:101], v[122:125]
	v_mfma_f32_16x16x32_bf16 v[32:35], v[20:23], v[102:105], v[130:133]
	v_cndmask_b32_e32 v20, v175, v176, vcc
	v_lshlrev_b32_e32 v68, 2, v20
	ds_bpermute_b32 v89, v68, v88
	v_cmp_lt_i32_e32 vcc, v74, v177
	s_waitcnt lgkmcnt(2)
	v_mfma_f32_16x16x32_bf16 v[20:23], v[106:109], v[64:67], v[134:137]
	s_waitcnt lgkmcnt(0)
	v_add_f32_e32 v88, v88, v89
	v_cndmask_b32_e32 v73, v175, v74, vcc
	v_lshlrev_b32_e32 v73, 2, v73
	ds_bpermute_b32 v89, v73, v88
	v_cmp_lt_i32_e32 vcc, v75, v177
	v_mfma_f32_16x16x32_bf16 v[12:15], v[110:113], v[64:67], v[12:15]
	s_waitcnt lgkmcnt(0)
	v_add_f32_e32 v67, v88, v89
	v_cndmask_b32_e32 v90, v175, v75, vcc
	v_lshlrev_b32_e32 v64, 2, v90
	ds_bpermute_b32 v88, v64, v67
	v_cmp_lt_i32_e32 vcc, v76, v177
	v_mfma_f32_16x16x32_bf16 v[24:27], v[106:109], v[94:97], v[138:141]
	s_waitcnt lgkmcnt(0)
	v_add_f32_e32 v67, v67, v88
	v_cndmask_b32_e32 v65, v175, v76, vcc
	v_lshlrev_b32_e32 v66, 2, v65
	ds_bpermute_b32 v88, v66, v67
	v_mfma_f32_16x16x32_bf16 v[28:31], v[106:109], v[98:101], v[28:31]
	v_cmp_eq_u32_e32 vcc, 0, v91
	v_lshl_add_u32 v65, v72, 2, v87
	v_mfma_f32_16x16x32_bf16 v[16:19], v[106:109], v[102:105], v[16:19]
	v_mfma_f32_16x16x32_bf16 v[4:7], v[110:113], v[94:97], v[4:7]
	v_mfma_f32_16x16x32_bf16 v[8:11], v[110:113], v[98:101], v[8:11]
	v_mfma_f32_16x16x32_bf16 v[0:3], v[110:113], v[102:105], v[0:3]
	s_and_saveexec_b64 s[0:1], vcc
	s_cbranch_execz .LBB0_487
	s_waitcnt lgkmcnt(0)
	v_add_f32_e32 v67, v67, v88
	ds_write_b32 v65, v67 offset:43008
